# v16 + first grid seam: per-XCD count polling hoisted above the workgroup store-drain wait and barrier
# speedup vs baseline: 1.0064x; 1.0022x over previous
; __device__ __forceinline__ unsigned xb_ld(unsigned* p)              { return __hip_atomic_load(p, __ATOMIC_RELAXED, __HIP_MEMORY_SCOPE_AGENT); }
; __device__ __forceinline__ void xcd_barrier_complete(unsigned* bar, unsigned x, unsigned& nloc, unsigned& nx) {
;     const unsigned G = 256u;
;     unsigned sum, cnt, mine, sp = 0u;
;     for (;;) {
;         sum = 0u; cnt = 0u; mine = 0u;
; #pragma unroll
;         for (unsigned j = 0; j < 16; ++j) { const unsigned c = xb_ld(&bar[XB_XCNT(j)]); sum += c; cnt += (c > 0u) ? 1u : 0u; mine = (j == x) ? c : mine; }
; __device__ __forceinline__ void xcd_barrier(const XcdBarrier& b) {
;     asm volatile("s_waitcnt vmcnt(0)" ::: "memory");
;     __syncthreads();
;     if (threadIdx.x == 0) {
;         unsigned* bar = b.bar;
;         __builtin_amdgcn_s_waitcnt(0);
;         unsigned nloc = b.st[0], nx = b.st[1];
;         if (nloc == 0u) { xcd_barrier_complete(bar, b.x, nloc, nx); b.st[0] = nloc; b.st[1] = nx; }
.LBB0_126:
	s_and_saveexec_b64 s[4:5], s[92:93]
	s_cbranch_execz .Lpre0_join
	s_add_i32 s0, 0, 0x22000
	v_mov_b32_e32 v1, s0
	s_waitcnt lgkmcnt(0)
	ds_read_b32 v3, v1
	s_add_i32 s0, 0, 0x22004
	v_mov_b32_e32 v1, s0
	ds_read_b32 v1, v1
	s_waitcnt lgkmcnt(1)
	v_cmp_ne_u32_e32 vcc, 0, v3
	s_cbranch_vccnz .Lpre0_join
	s_add_u32 s6, s78, 0xbd00200
	s_addc_u32 s7, s79, 0
	s_add_u32 s8, s78, 0xbd00400
	s_addc_u32 s9, s79, 0
	s_add_u32 s12, s78, 0xbd00500
	s_addc_u32 s13, s79, 0
	s_add_u32 s14, s78, 0xbd00600
	s_addc_u32 s15, s79, 0
	s_add_u32 s16, s78, 0xbd00700
	s_addc_u32 s17, s79, 0
	s_add_u32 s18, s78, 0xbd00800
	s_addc_u32 s19, s79, 0
	s_add_u32 s20, s78, 0xbd00900
	s_addc_u32 s21, s79, 0
	s_add_u32 s22, s78, 0xbd00a00
	s_addc_u32 s23, s79, 0
	s_add_u32 s24, s78, 0xbd00b00
	s_addc_u32 s25, s79, 0
	s_add_u32 s26, s78, 0xbd00c00
	s_addc_u32 s27, s79, 0
	s_add_u32 s28, s78, 0xbd00d00
	s_addc_u32 s29, s79, 0
	s_add_u32 s30, s78, 0xbd00e00
	s_addc_u32 s31, s79, 0
	s_add_u32 s34, s78, 0xbd00f00
	s_addc_u32 s35, s79, 0
	s_add_u32 s36, s78, 0xbd01000
	s_addc_u32 s37, s79, 0
	s_add_u32 s38, s78, 0xbd01100
	s_addc_u32 s39, s79, 0
	s_add_u32 s40, s78, 0xbd01200
	s_addc_u32 s41, s79, 0
	s_add_u32 s42, s78, 0xbd01300
	s_addc_u32 s43, s79, 0
	s_mov_b32 s0, 1
	v_mov_b32_e32 v17, 0
	s_movk_i32 s1, 0x100
	s_branch .LBB0_130

; __device__ __forceinline__ void xcd_barrier(const XcdBarrier& b) {
;     asm volatile("s_waitcnt vmcnt(0)" ::: "memory");
;     __syncthreads();
;     if (threadIdx.x == 0) {
.Lpre0_join:
	s_or_b64 exec, exec, s[4:5]
	s_waitcnt vmcnt(0)
	s_waitcnt lgkmcnt(0)
	s_barrier
	s_and_saveexec_b64 s[4:5], s[92:93]
	s_cbranch_execz .LBB0_178
